# P2 key-mean item: the 256 row loads per lane software-pipelined (three groups of 16 in flight, same partial sums and order of additions)
# speedup vs baseline: 1.0100x; 1.0013x over previous
.LBB0_232:
	s_lshl_b32 s40, s36, 8
	s_ashr_i32 s41, s40, 31
	s_lshl_b32 s38, s87, 7
	s_lshl_b64 s[0:1], s[40:41], 11
	s_add_u32 s42, s64, s0
	v_mov_b32_e32 v14, v199
	s_addc_u32 s43, s65, s1
	s_ashr_i32 s39, s38, 31
	s_lshl_b64 s[0:1], s[38:39], 11
	v_ashrrev_i32_e32 v2, 2, v14
	v_lshrrev_b32_e32 v15, 4, v14
	v_xor_b32_e32 v6, v15, v14
	s_add_u32 s44, s84, s0
	v_lshlrev_b32_e32 v6, 4, v6
	s_addc_u32 s45, s85, s1
	v_and_b32_e32 v6, 48, v6
	v_lshl_add_u32 v183, v14, 4, 0
	v_lshl_or_b32 v224, v2, 11, v6
	v_add_u32_e32 v225, 0x20000, v224
	v_add_u32_e32 v226, 0x40000, v224
	v_add_u32_e32 v227, 0x60000, v224
	v_lshrrev_b32_e32 v8, 5, v14
	v_bfe_u32 v9, v14, 5, 1
	v_readfirstlane_b32 s48, v183
	v_bfe_u32 v6, v14, 2, 2
	v_bitop3_b32 v17, v8, v6, 1 bitop3:0x6c
	v_bitop3_b32 v18, v9, v6, 2 bitop3:0x36
	v_lshlrev_b32_e32 v16, 6, v14
	v_and_b32_e32 v184, 0xffffe7c0, v16
	v_lshl_add_u32 v185, v17, 4, 0
	v_and_b32_e32 v182, 0x17c0, v16
	v_lshl_add_u32 v186, v18, 4, 0
	v_lshlrev_b32_e32 v222, 4, v14
	s_mov_b64 s[98:99], s[42:43]
	s_mov_b64 s[100:101], s[44:45]
	s_add_u32 s0, s42, 64
	s_addc_u32 s1, s43, 0
	s_add_u32 s12, s44, 64
	s_addc_u32 s13, s45, 0
	s_barrier
	s_add_u32 m0, s48, 0x0
	v_mov_b32_e32 v2, 0
	global_load_lds_dwordx4 v224, s[98:99]
	s_add_u32 m0, s48, 0x6000
	v_mov_b32_e32 v3, 0
	global_load_lds_dwordx4 v224, s[0:1]
	s_add_u32 m0, s48, 0x1000
	v_mov_b32_e32 v4, 0
	global_load_lds_dwordx4 v225, s[98:99]
	s_add_u32 m0, s48, 0x7000
	v_mov_b32_e32 v5, 0
	global_load_lds_dwordx4 v225, s[0:1]
	s_add_u32 m0, s48, 0x2000
	v_mov_b32_e32 v6, 0
	global_load_lds_dwordx4 v226, s[98:99]
	s_add_u32 m0, s48, 0x8000
	v_mov_b32_e32 v7, 0
	global_load_lds_dwordx4 v226, s[0:1]
	s_add_u32 m0, s48, 0x3000
	v_mov_b32_e32 v8, 0
	global_load_lds_dwordx4 v227, s[98:99]
	s_add_u32 m0, s48, 0x9000
	v_mov_b32_e32 v9, 0
	global_load_lds_dwordx4 v227, s[0:1]
	s_add_u32 m0, s48, 0x4000
	v_mov_b32_e32 v10, 0
	global_load_lds_dwordx4 v224, s[100:101]
	s_add_u32 m0, s48, 0xa000
	v_mov_b32_e32 v11, 0
	global_load_lds_dwordx4 v224, s[12:13]
	s_add_u32 m0, s48, 0x5000
	v_mov_b32_e32 v12, 0
	global_load_lds_dwordx4 v225, s[100:101]
	s_add_u32 m0, s48, 0xb000
	v_mov_b32_e32 v13, 0
	global_load_lds_dwordx4 v225, s[12:13]
	s_add_u32 s98, s98, 0x80
	s_addc_u32 s99, s99, 0
	s_add_u32 s100, s100, 0x80
	s_addc_u32 s101, s101, 0
	s_add_u32 s0, s0, 0x80
	s_addc_u32 s1, s1, 0
	s_add_u32 s12, s12, 0x80
	s_addc_u32 s13, s13, 0
	v_mov_b32_e32 v14, 0
	v_mov_b32_e32 v15, 0
	v_mov_b32_e32 v16, 0
	v_mov_b32_e32 v17, 0
	v_mov_b32_e32 v18, 0
	v_mov_b32_e32 v19, 0
	v_mov_b32_e32 v20, 0
	v_mov_b32_e32 v21, 0
	v_mov_b32_e32 v22, 0
	v_mov_b32_e32 v23, 0
	v_mov_b32_e32 v24, 0
	v_mov_b32_e32 v25, 0
	v_mov_b32_e32 v26, 0
	v_mov_b32_e32 v27, 0
	v_mov_b32_e32 v28, 0
	v_mov_b32_e32 v29, 0
	v_mov_b32_e32 v30, 0
	v_mov_b32_e32 v31, 0
	v_mov_b32_e32 v32, 0
	v_mov_b32_e32 v33, 0
	v_mov_b32_e32 v34, 0
	v_mov_b32_e32 v35, 0
	v_mov_b32_e32 v36, 0
	v_mov_b32_e32 v37, 0
	v_mov_b32_e32 v38, 0
	v_mov_b32_e32 v39, 0
	v_mov_b32_e32 v40, 0
	v_mov_b32_e32 v41, 0
	v_mov_b32_e32 v42, 0
	v_mov_b32_e32 v43, 0
	v_mov_b32_e32 v44, 0
	v_mov_b32_e32 v45, 0
	v_mov_b32_e32 v46, 0
	v_mov_b32_e32 v47, 0
	v_mov_b32_e32 v48, 0
	v_mov_b32_e32 v49, 0
	v_mov_b32_e32 v50, 0
	v_mov_b32_e32 v51, 0
	v_mov_b32_e32 v52, 0
	v_mov_b32_e32 v53, 0
	v_mov_b32_e32 v54, 0
	v_mov_b32_e32 v55, 0
	v_mov_b32_e32 v56, 0
	v_mov_b32_e32 v57, 0
	v_mov_b32_e32 v58, 0
	v_mov_b32_e32 v59, 0
	v_mov_b32_e32 v60, 0
	v_mov_b32_e32 v61, 0
	v_mov_b32_e32 v62, 0
	v_mov_b32_e32 v63, 0
	v_mov_b32_e32 v64, 0
	v_mov_b32_e32 v65, 0
	v_mov_b32_e32 v66, 0
	v_mov_b32_e32 v67, 0
	v_mov_b32_e32 v68, 0
	v_mov_b32_e32 v69, 0
	v_mov_b32_e32 v70, 0
	v_mov_b32_e32 v71, 0
	v_mov_b32_e32 v72, 0
	v_mov_b32_e32 v73, 0
	v_mov_b32_e32 v74, 0
	v_mov_b32_e32 v75, 0
	v_mov_b32_e32 v76, 0
	v_mov_b32_e32 v77, 0
	v_mov_b32_e32 v78, 0
	v_mov_b32_e32 v79, 0
	v_mov_b32_e32 v80, 0
	v_mov_b32_e32 v81, 0
	v_mov_b32_e32 v82, 0
	v_mov_b32_e32 v83, 0
	v_mov_b32_e32 v84, 0
	v_mov_b32_e32 v85, 0
	v_mov_b32_e32 v86, 0
	v_mov_b32_e32 v87, 0
	v_mov_b32_e32 v88, 0
	v_mov_b32_e32 v89, 0
	v_mov_b32_e32 v90, 0
	v_mov_b32_e32 v91, 0
	v_mov_b32_e32 v92, 0
	v_mov_b32_e32 v93, 0
	v_mov_b32_e32 v94, 0
	v_mov_b32_e32 v95, 0
	v_mov_b32_e32 v96, 0
	v_mov_b32_e32 v97, 0
	v_mov_b32_e32 v98, 0
	v_mov_b32_e32 v99, 0
	v_mov_b32_e32 v100, 0
	v_mov_b32_e32 v101, 0
	v_mov_b32_e32 v102, 0
	v_mov_b32_e32 v103, 0
	v_mov_b32_e32 v104, 0
	v_mov_b32_e32 v105, 0
	v_mov_b32_e32 v106, 0
	v_mov_b32_e32 v107, 0
	v_mov_b32_e32 v108, 0
	v_mov_b32_e32 v109, 0
	v_mov_b32_e32 v110, 0
	v_mov_b32_e32 v111, 0
	v_mov_b32_e32 v112, 0
	v_mov_b32_e32 v113, 0
	v_mov_b32_e32 v114, 0
	v_mov_b32_e32 v115, 0
	v_mov_b32_e32 v116, 0
	v_mov_b32_e32 v117, 0
	v_mov_b32_e32 v118, 0
	v_mov_b32_e32 v119, 0
	v_mov_b32_e32 v120, 0
	v_mov_b32_e32 v121, 0
	v_mov_b32_e32 v122, 0
	v_mov_b32_e32 v123, 0
	v_mov_b32_e32 v124, 0
	v_mov_b32_e32 v125, 0
	v_mov_b32_e32 v126, 0
	v_mov_b32_e32 v127, 0
	v_mov_b32_e32 v128, 0
	v_mov_b32_e32 v129, 0
	s_mov_b32 s42, 0
	s_movk_i32 s43, 0x6000
	s_mov_b32 s44, 0xc000
	s_mov_b32 s41, 0
	v_add_u32_e32 v229, v185, v182
	v_add_u32_e32 v228, v185, v184
	s_waitcnt vmcnt(0)
	s_barrier
	ds_read_b128 v[130:133], v228
	ds_read_b128 v[134:137], v228 offset:2048
	ds_read_b128 v[138:141], v228 offset:4096
	ds_read_b128 v[142:145], v228 offset:6144
	ds_read_b128 v[146:149], v229 offset:16384
	ds_read_b128 v[150:153], v229 offset:18432

.LBB0_386:
	v_lshlrev_b32_e32 v9, 1, v2
	v_add_u32_e32 v9, 0xfffe5c00, v9
	v_mov_b32_e32 v58, v9
	global_load_ushort v10, v58, s[66:67]
	v_add_u32_e32 v59, 0x1c00, v9
	global_load_ushort v11, v59, s[66:67]
	v_add_u32_e32 v58, 0x3800, v9
	global_load_ushort v12, v58, s[66:67]
	v_add_u32_e32 v59, 0x5400, v9
	global_load_ushort v13, v59, s[66:67]
	v_add_u32_e32 v58, 0x7000, v9
	global_load_ushort v14, v58, s[66:67]
	v_add_u32_e32 v59, 0x8c00, v9
	global_load_ushort v15, v59, s[66:67]
	v_add_u32_e32 v58, 0xa800, v9
	global_load_ushort v16, v58, s[66:67]
	v_add_u32_e32 v59, 0xc400, v9
	global_load_ushort v17, v59, s[66:67]
	v_add_u32_e32 v58, 0xe000, v9
	global_load_ushort v18, v58, s[66:67]
	v_add_u32_e32 v59, 0xfc00, v9
	global_load_ushort v19, v59, s[66:67]
	v_add_u32_e32 v58, 0x11800, v9
	global_load_ushort v20, v58, s[66:67]
	v_add_u32_e32 v59, 0x13400, v9
	global_load_ushort v21, v59, s[66:67]
	v_add_u32_e32 v58, 0x15000, v9
	global_load_ushort v22, v58, s[66:67]
	v_add_u32_e32 v59, 0x16c00, v9
	global_load_ushort v23, v59, s[66:67]
	v_add_u32_e32 v58, 0x18800, v9
	global_load_ushort v24, v58, s[66:67]
	v_add_u32_e32 v59, 0x1a400, v9
	global_load_ushort v25, v59, s[66:67]
	v_add_u32_e32 v9, 0x1c000, v9
	v_mov_b32_e32 v58, v9
	global_load_ushort v26, v58, s[66:67]
	v_add_u32_e32 v59, 0x1c00, v9
	global_load_ushort v27, v59, s[66:67]
	v_add_u32_e32 v58, 0x3800, v9
	global_load_ushort v28, v58, s[66:67]
	v_add_u32_e32 v59, 0x5400, v9
	global_load_ushort v29, v59, s[66:67]
	v_add_u32_e32 v58, 0x7000, v9
	global_load_ushort v30, v58, s[66:67]
	v_add_u32_e32 v59, 0x8c00, v9
	global_load_ushort v31, v59, s[66:67]
	v_add_u32_e32 v58, 0xa800, v9
	global_load_ushort v32, v58, s[66:67]
	v_add_u32_e32 v59, 0xc400, v9
	global_load_ushort v33, v59, s[66:67]
	v_add_u32_e32 v58, 0xe000, v9
	global_load_ushort v34, v58, s[66:67]
	v_add_u32_e32 v59, 0xfc00, v9
	global_load_ushort v35, v59, s[66:67]
	v_add_u32_e32 v58, 0x11800, v9
	global_load_ushort v36, v58, s[66:67]
	v_add_u32_e32 v59, 0x13400, v9
	global_load_ushort v37, v59, s[66:67]
	v_add_u32_e32 v58, 0x15000, v9
	global_load_ushort v38, v58, s[66:67]
	v_add_u32_e32 v59, 0x16c00, v9
	global_load_ushort v39, v59, s[66:67]
	v_add_u32_e32 v58, 0x18800, v9
	global_load_ushort v40, v58, s[66:67]
	v_add_u32_e32 v59, 0x1a400, v9
	global_load_ushort v41, v59, s[66:67]
	v_add_u32_e32 v9, 0x1c000, v9
	v_mov_b32_e32 v58, v9
	global_load_ushort v42, v58, s[66:67]
	v_add_u32_e32 v59, 0x1c00, v9
	global_load_ushort v43, v59, s[66:67]
	v_add_u32_e32 v58, 0x3800, v9
	global_load_ushort v44, v58, s[66:67]
	v_add_u32_e32 v59, 0x5400, v9
	global_load_ushort v45, v59, s[66:67]
	v_add_u32_e32 v58, 0x7000, v9
	global_load_ushort v46, v58, s[66:67]
	v_add_u32_e32 v59, 0x8c00, v9
	global_load_ushort v47, v59, s[66:67]
	v_add_u32_e32 v58, 0xa800, v9
	global_load_ushort v48, v58, s[66:67]
	v_add_u32_e32 v59, 0xc400, v9
	global_load_ushort v49, v59, s[66:67]
	v_add_u32_e32 v58, 0xe000, v9
	global_load_ushort v50, v58, s[66:67]
	v_add_u32_e32 v59, 0xfc00, v9
	global_load_ushort v51, v59, s[66:67]
	v_add_u32_e32 v58, 0x11800, v9
	global_load_ushort v52, v58, s[66:67]
	v_add_u32_e32 v59, 0x13400, v9
	global_load_ushort v53, v59, s[66:67]
	v_add_u32_e32 v58, 0x15000, v9
	global_load_ushort v54, v58, s[66:67]
	v_add_u32_e32 v59, 0x16c00, v9
	global_load_ushort v55, v59, s[66:67]
	v_add_u32_e32 v58, 0x18800, v9
	global_load_ushort v56, v58, s[66:67]
	v_add_u32_e32 v59, 0x1a400, v9
	global_load_ushort v57, v59, s[66:67]
	v_add_u32_e32 v9, 0x1c000, v9
	s_waitcnt vmcnt(32)
	v_lshlrev_b32_e32 v10, 16, v10
	v_lshlrev_b32_e32 v11, 16, v11
	v_lshlrev_b32_e32 v12, 16, v12
	v_lshlrev_b32_e32 v13, 16, v13
	v_lshlrev_b32_e32 v14, 16, v14
	v_lshlrev_b32_e32 v15, 16, v15
	v_lshlrev_b32_e32 v16, 16, v16
	v_lshlrev_b32_e32 v17, 16, v17
	v_lshlrev_b32_e32 v18, 16, v18
	v_lshlrev_b32_e32 v19, 16, v19
	v_lshlrev_b32_e32 v20, 16, v20
	v_lshlrev_b32_e32 v21, 16, v21
	v_lshlrev_b32_e32 v22, 16, v22
	v_lshlrev_b32_e32 v23, 16, v23
	v_lshlrev_b32_e32 v24, 16, v24
	v_lshlrev_b32_e32 v25, 16, v25
	v_add_f32_e32 v4, v4, v10
	v_add_f32_e32 v6, v6, v11
	v_add_f32_e32 v5, v5, v12
	v_add_f32_e32 v7, v7, v13
	v_add_f32_e32 v4, v4, v14
	v_add_f32_e32 v6, v6, v15
	v_add_f32_e32 v5, v5, v16
	v_add_f32_e32 v7, v7, v17
	v_add_f32_e32 v4, v4, v18
	v_add_f32_e32 v6, v6, v19
	v_add_f32_e32 v5, v5, v20
	v_add_f32_e32 v7, v7, v21
	v_add_f32_e32 v4, v4, v22
	v_add_f32_e32 v6, v6, v23
	v_add_f32_e32 v5, v5, v24
	v_add_f32_e32 v7, v7, v25
	v_mov_b32_e32 v58, v9
	global_load_ushort v10, v58, s[66:67]
	v_add_u32_e32 v59, 0x1c00, v9
	global_load_ushort v11, v59, s[66:67]
	v_add_u32_e32 v58, 0x3800, v9
	global_load_ushort v12, v58, s[66:67]
	v_add_u32_e32 v59, 0x5400, v9
	global_load_ushort v13, v59, s[66:67]
	v_add_u32_e32 v58, 0x7000, v9
	global_load_ushort v14, v58, s[66:67]
	v_add_u32_e32 v59, 0x8c00, v9
	global_load_ushort v15, v59, s[66:67]
	v_add_u32_e32 v58, 0xa800, v9
	global_load_ushort v16, v58, s[66:67]
	v_add_u32_e32 v59, 0xc400, v9
	global_load_ushort v17, v59, s[66:67]
	v_add_u32_e32 v58, 0xe000, v9
	global_load_ushort v18, v58, s[66:67]
	v_add_u32_e32 v59, 0xfc00, v9
	global_load_ushort v19, v59, s[66:67]
	v_add_u32_e32 v58, 0x11800, v9
	global_load_ushort v20, v58, s[66:67]
	v_add_u32_e32 v59, 0x13400, v9
	global_load_ushort v21, v59, s[66:67]
	v_add_u32_e32 v58, 0x15000, v9
	global_load_ushort v22, v58, s[66:67]
	v_add_u32_e32 v59, 0x16c00, v9
	global_load_ushort v23, v59, s[66:67]
	v_add_u32_e32 v58, 0x18800, v9
	global_load_ushort v24, v58, s[66:67]
	v_add_u32_e32 v59, 0x1a400, v9
	global_load_ushort v25, v59, s[66:67]
	v_add_u32_e32 v9, 0x1c000, v9
	s_waitcnt vmcnt(32)
	v_lshlrev_b32_e32 v26, 16, v26
	v_lshlrev_b32_e32 v27, 16, v27
	v_lshlrev_b32_e32 v28, 16, v28
	v_lshlrev_b32_e32 v29, 16, v29
	v_lshlrev_b32_e32 v30, 16, v30
	v_lshlrev_b32_e32 v31, 16, v31
	v_lshlrev_b32_e32 v32, 16, v32
	v_lshlrev_b32_e32 v33, 16, v33
	v_lshlrev_b32_e32 v34, 16, v34
	v_lshlrev_b32_e32 v35, 16, v35
	v_lshlrev_b32_e32 v36, 16, v36
	v_lshlrev_b32_e32 v37, 16, v37
	v_lshlrev_b32_e32 v38, 16, v38
	v_lshlrev_b32_e32 v39, 16, v39
	v_lshlrev_b32_e32 v40, 16, v40
	v_lshlrev_b32_e32 v41, 16, v41
	v_add_f32_e32 v4, v4, v26
	v_add_f32_e32 v6, v6, v27
	v_add_f32_e32 v5, v5, v28
	v_add_f32_e32 v7, v7, v29
	v_add_f32_e32 v4, v4, v30
	v_add_f32_e32 v6, v6, v31
	v_add_f32_e32 v5, v5, v32
	v_add_f32_e32 v7, v7, v33
	v_add_f32_e32 v4, v4, v34
	v_add_f32_e32 v6, v6, v35
	v_add_f32_e32 v5, v5, v36
	v_add_f32_e32 v7, v7, v37
	v_add_f32_e32 v4, v4, v38
	v_add_f32_e32 v6, v6, v39
	v_add_f32_e32 v5, v5, v40
	v_add_f32_e32 v7, v7, v41
	v_mov_b32_e32 v58, v9
	global_load_ushort v26, v58, s[66:67]
	v_add_u32_e32 v59, 0x1c00, v9
	global_load_ushort v27, v59, s[66:67]
	v_add_u32_e32 v58, 0x3800, v9
	global_load_ushort v28, v58, s[66:67]
	v_add_u32_e32 v59, 0x5400, v9
	global_load_ushort v29, v59, s[66:67]
	v_add_u32_e32 v58, 0x7000, v9
	global_load_ushort v30, v58, s[66:67]
	v_add_u32_e32 v59, 0x8c00, v9
	global_load_ushort v31, v59, s[66:67]
	v_add_u32_e32 v58, 0xa800, v9
	global_load_ushort v32, v58, s[66:67]
	v_add_u32_e32 v59, 0xc400, v9
	global_load_ushort v33, v59, s[66:67]
	v_add_u32_e32 v58, 0xe000, v9
	global_load_ushort v34, v58, s[66:67]
	v_add_u32_e32 v59, 0xfc00, v9
	global_load_ushort v35, v59, s[66:67]
	v_add_u32_e32 v58, 0x11800, v9
	global_load_ushort v36, v58, s[66:67]
	v_add_u32_e32 v59, 0x13400, v9
	global_load_ushort v37, v59, s[66:67]
	v_add_u32_e32 v58, 0x15000, v9
	global_load_ushort v38, v58, s[66:67]
	v_add_u32_e32 v59, 0x16c00, v9
	global_load_ushort v39, v59, s[66:67]
	v_add_u32_e32 v58, 0x18800, v9
	global_load_ushort v40, v58, s[66:67]
	v_add_u32_e32 v59, 0x1a400, v9
	global_load_ushort v41, v59, s[66:67]
	v_add_u32_e32 v9, 0x1c000, v9
	s_waitcnt vmcnt(32)
	v_lshlrev_b32_e32 v42, 16, v42
	v_lshlrev_b32_e32 v43, 16, v43
	v_lshlrev_b32_e32 v44, 16, v44
	v_lshlrev_b32_e32 v45, 16, v45
	v_lshlrev_b32_e32 v46, 16, v46
	v_lshlrev_b32_e32 v47, 16, v47
	v_lshlrev_b32_e32 v48, 16, v48
	v_lshlrev_b32_e32 v49, 16, v49
	v_lshlrev_b32_e32 v50, 16, v50
	v_lshlrev_b32_e32 v51, 16, v51
	v_lshlrev_b32_e32 v52, 16, v52
	v_lshlrev_b32_e32 v53, 16, v53
	v_lshlrev_b32_e32 v54, 16, v54
	v_lshlrev_b32_e32 v55, 16, v55
	v_lshlrev_b32_e32 v56, 16, v56
	v_lshlrev_b32_e32 v57, 16, v57
	v_add_f32_e32 v4, v4, v42
	v_add_f32_e32 v6, v6, v43
	v_add_f32_e32 v5, v5, v44
	v_add_f32_e32 v7, v7, v45
	v_add_f32_e32 v4, v4, v46
	v_add_f32_e32 v6, v6, v47
	v_add_f32_e32 v5, v5, v48
	v_add_f32_e32 v7, v7, v49
	v_add_f32_e32 v4, v4, v50
	v_add_f32_e32 v6, v6, v51
	v_add_f32_e32 v5, v5, v52
	v_add_f32_e32 v7, v7, v53
	v_add_f32_e32 v4, v4, v54
	v_add_f32_e32 v6, v6, v55
	v_add_f32_e32 v5, v5, v56
	v_add_f32_e32 v7, v7, v57
	v_mov_b32_e32 v58, v9
	global_load_ushort v42, v58, s[66:67]
	v_add_u32_e32 v59, 0x1c00, v9
	global_load_ushort v43, v59, s[66:67]
	v_add_u32_e32 v58, 0x3800, v9
	global_load_ushort v44, v58, s[66:67]
	v_add_u32_e32 v59, 0x5400, v9
	global_load_ushort v45, v59, s[66:67]
	v_add_u32_e32 v58, 0x7000, v9
	global_load_ushort v46, v58, s[66:67]
	v_add_u32_e32 v59, 0x8c00, v9
	global_load_ushort v47, v59, s[66:67]
	v_add_u32_e32 v58, 0xa800, v9
	global_load_ushort v48, v58, s[66:67]
	v_add_u32_e32 v59, 0xc400, v9
	global_load_ushort v49, v59, s[66:67]
	v_add_u32_e32 v58, 0xe000, v9
	global_load_ushort v50, v58, s[66:67]
	v_add_u32_e32 v59, 0xfc00, v9
	global_load_ushort v51, v59, s[66:67]
	v_add_u32_e32 v58, 0x11800, v9
	global_load_ushort v52, v58, s[66:67]
	v_add_u32_e32 v59, 0x13400, v9
	global_load_ushort v53, v59, s[66:67]
	v_add_u32_e32 v58, 0x15000, v9
	global_load_ushort v54, v58, s[66:67]
	v_add_u32_e32 v59, 0x16c00, v9
	global_load_ushort v55, v59, s[66:67]
	v_add_u32_e32 v58, 0x18800, v9
	global_load_ushort v56, v58, s[66:67]
	v_add_u32_e32 v59, 0x1a400, v9
	global_load_ushort v57, v59, s[66:67]
	v_add_u32_e32 v9, 0x1c000, v9
	s_waitcnt vmcnt(32)
	v_lshlrev_b32_e32 v10, 16, v10
	v_lshlrev_b32_e32 v11, 16, v11
	v_lshlrev_b32_e32 v12, 16, v12
	v_lshlrev_b32_e32 v13, 16, v13
	v_lshlrev_b32_e32 v14, 16, v14
	v_lshlrev_b32_e32 v15, 16, v15
	v_lshlrev_b32_e32 v16, 16, v16
	v_lshlrev_b32_e32 v17, 16, v17
	v_lshlrev_b32_e32 v18, 16, v18
	v_lshlrev_b32_e32 v19, 16, v19
	v_lshlrev_b32_e32 v20, 16, v20
	v_lshlrev_b32_e32 v21, 16, v21
	v_lshlrev_b32_e32 v22, 16, v22
	v_lshlrev_b32_e32 v23, 16, v23
	v_lshlrev_b32_e32 v24, 16, v24
	v_lshlrev_b32_e32 v25, 16, v25
	v_add_f32_e32 v4, v4, v10
	v_add_f32_e32 v6, v6, v11
	v_add_f32_e32 v5, v5, v12
	v_add_f32_e32 v7, v7, v13
	v_add_f32_e32 v4, v4, v14
	v_add_f32_e32 v6, v6, v15
	v_add_f32_e32 v5, v5, v16
	v_add_f32_e32 v7, v7, v17
	v_add_f32_e32 v4, v4, v18
	v_add_f32_e32 v6, v6, v19
	v_add_f32_e32 v5, v5, v20
	v_add_f32_e32 v7, v7, v21
	v_add_f32_e32 v4, v4, v22
	v_add_f32_e32 v6, v6, v23
	v_add_f32_e32 v5, v5, v24
	v_add_f32_e32 v7, v7, v25
	v_mov_b32_e32 v58, v9
	global_load_ushort v10, v58, s[66:67]
	v_add_u32_e32 v59, 0x1c00, v9
	global_load_ushort v11, v59, s[66:67]
	v_add_u32_e32 v58, 0x3800, v9
	global_load_ushort v12, v58, s[66:67]
	v_add_u32_e32 v59, 0x5400, v9
	global_load_ushort v13, v59, s[66:67]
	v_add_u32_e32 v58, 0x7000, v9
	global_load_ushort v14, v58, s[66:67]
	v_add_u32_e32 v59, 0x8c00, v9
	global_load_ushort v15, v59, s[66:67]
	v_add_u32_e32 v58, 0xa800, v9
	global_load_ushort v16, v58, s[66:67]
	v_add_u32_e32 v59, 0xc400, v9
	global_load_ushort v17, v59, s[66:67]
	v_add_u32_e32 v58, 0xe000, v9
	global_load_ushort v18, v58, s[66:67]
	v_add_u32_e32 v59, 0xfc00, v9
	global_load_ushort v19, v59, s[66:67]
	v_add_u32_e32 v58, 0x11800, v9
	global_load_ushort v20, v58, s[66:67]
	v_add_u32_e32 v59, 0x13400, v9
	global_load_ushort v21, v59, s[66:67]
	v_add_u32_e32 v58, 0x15000, v9
	global_load_ushort v22, v58, s[66:67]
	v_add_u32_e32 v59, 0x16c00, v9
	global_load_ushort v23, v59, s[66:67]
	v_add_u32_e32 v58, 0x18800, v9
	global_load_ushort v24, v58, s[66:67]
	v_add_u32_e32 v59, 0x1a400, v9
	global_load_ushort v25, v59, s[66:67]
	v_add_u32_e32 v9, 0x1c000, v9
	s_waitcnt vmcnt(32)
	v_lshlrev_b32_e32 v26, 16, v26
	v_lshlrev_b32_e32 v27, 16, v27
	v_lshlrev_b32_e32 v28, 16, v28
	v_lshlrev_b32_e32 v29, 16, v29
	v_lshlrev_b32_e32 v30, 16, v30
	v_lshlrev_b32_e32 v31, 16, v31
	v_lshlrev_b32_e32 v32, 16, v32
	v_lshlrev_b32_e32 v33, 16, v33
	v_lshlrev_b32_e32 v34, 16, v34
	v_lshlrev_b32_e32 v35, 16, v35
	v_lshlrev_b32_e32 v36, 16, v36
	v_lshlrev_b32_e32 v37, 16, v37
	v_lshlrev_b32_e32 v38, 16, v38
	v_lshlrev_b32_e32 v39, 16, v39
	v_lshlrev_b32_e32 v40, 16, v40
	v_lshlrev_b32_e32 v41, 16, v41
	v_add_f32_e32 v4, v4, v26
	v_add_f32_e32 v6, v6, v27
	v_add_f32_e32 v5, v5, v28
	v_add_f32_e32 v7, v7, v29
	v_add_f32_e32 v4, v4, v30
	v_add_f32_e32 v6, v6, v31
	v_add_f32_e32 v5, v5, v32
	v_add_f32_e32 v7, v7, v33
	v_add_f32_e32 v4, v4, v34
	v_add_f32_e32 v6, v6, v35
	v_add_f32_e32 v5, v5, v36
	v_add_f32_e32 v7, v7, v37
	v_add_f32_e32 v4, v4, v38
	v_add_f32_e32 v6, v6, v39
	v_add_f32_e32 v5, v5, v40
	v_add_f32_e32 v7, v7, v41
	v_mov_b32_e32 v58, v9
	global_load_ushort v26, v58, s[66:67]
	v_add_u32_e32 v59, 0x1c00, v9
	global_load_ushort v27, v59, s[66:67]
	v_add_u32_e32 v58, 0x3800, v9
	global_load_ushort v28, v58, s[66:67]
	v_add_u32_e32 v59, 0x5400, v9
	global_load_ushort v29, v59, s[66:67]
	v_add_u32_e32 v58, 0x7000, v9
	global_load_ushort v30, v58, s[66:67]
	v_add_u32_e32 v59, 0x8c00, v9
	global_load_ushort v31, v59, s[66:67]
	v_add_u32_e32 v58, 0xa800, v9
	global_load_ushort v32, v58, s[66:67]
	v_add_u32_e32 v59, 0xc400, v9
	global_load_ushort v33, v59, s[66:67]
	v_add_u32_e32 v58, 0xe000, v9
	global_load_ushort v34, v58, s[66:67]
	v_add_u32_e32 v59, 0xfc00, v9
	global_load_ushort v35, v59, s[66:67]
	v_add_u32_e32 v58, 0x11800, v9
	global_load_ushort v36, v58, s[66:67]
	v_add_u32_e32 v59, 0x13400, v9
	global_load_ushort v37, v59, s[66:67]
	v_add_u32_e32 v58, 0x15000, v9
	global_load_ushort v38, v58, s[66:67]
	v_add_u32_e32 v59, 0x16c00, v9
	global_load_ushort v39, v59, s[66:67]
	v_add_u32_e32 v58, 0x18800, v9
	global_load_ushort v40, v58, s[66:67]
	v_add_u32_e32 v59, 0x1a400, v9
	global_load_ushort v41, v59, s[66:67]
	v_add_u32_e32 v9, 0x1c000, v9
	s_waitcnt vmcnt(32)
	v_lshlrev_b32_e32 v42, 16, v42
	v_lshlrev_b32_e32 v43, 16, v43
	v_lshlrev_b32_e32 v44, 16, v44
	v_lshlrev_b32_e32 v45, 16, v45
	v_lshlrev_b32_e32 v46, 16, v46
	v_lshlrev_b32_e32 v47, 16, v47
	v_lshlrev_b32_e32 v48, 16, v48
	v_lshlrev_b32_e32 v49, 16, v49
	v_lshlrev_b32_e32 v50, 16, v50
	v_lshlrev_b32_e32 v51, 16, v51
	v_lshlrev_b32_e32 v52, 16, v52
	v_lshlrev_b32_e32 v53, 16, v53
	v_lshlrev_b32_e32 v54, 16, v54
	v_lshlrev_b32_e32 v55, 16, v55
	v_lshlrev_b32_e32 v56, 16, v56
	v_lshlrev_b32_e32 v57, 16, v57
	v_add_f32_e32 v4, v4, v42
	v_add_f32_e32 v6, v6, v43
	v_add_f32_e32 v5, v5, v44
	v_add_f32_e32 v7, v7, v45
	v_add_f32_e32 v4, v4, v46
	v_add_f32_e32 v6, v6, v47
	v_add_f32_e32 v5, v5, v48
	v_add_f32_e32 v7, v7, v49
	v_add_f32_e32 v4, v4, v50
	v_add_f32_e32 v6, v6, v51
	v_add_f32_e32 v5, v5, v52
	v_add_f32_e32 v7, v7, v53
	v_add_f32_e32 v4, v4, v54
	v_add_f32_e32 v6, v6, v55
	v_add_f32_e32 v5, v5, v56
	v_add_f32_e32 v7, v7, v57
	v_mov_b32_e32 v58, v9
	global_load_ushort v42, v58, s[66:67]
	v_add_u32_e32 v59, 0x1c00, v9
	global_load_ushort v43, v59, s[66:67]
	v_add_u32_e32 v58, 0x3800, v9
	global_load_ushort v44, v58, s[66:67]
	v_add_u32_e32 v59, 0x5400, v9
	global_load_ushort v45, v59, s[66:67]
	v_add_u32_e32 v58, 0x7000, v9
	global_load_ushort v46, v58, s[66:67]
	v_add_u32_e32 v59, 0x8c00, v9
	global_load_ushort v47, v59, s[66:67]
	v_add_u32_e32 v58, 0xa800, v9
	global_load_ushort v48, v58, s[66:67]
	v_add_u32_e32 v59, 0xc400, v9
	global_load_ushort v49, v59, s[66:67]
	v_add_u32_e32 v58, 0xe000, v9
	global_load_ushort v50, v58, s[66:67]
	v_add_u32_e32 v59, 0xfc00, v9
	global_load_ushort v51, v59, s[66:67]
	v_add_u32_e32 v58, 0x11800, v9
	global_load_ushort v52, v58, s[66:67]
	v_add_u32_e32 v59, 0x13400, v9
	global_load_ushort v53, v59, s[66:67]
	v_add_u32_e32 v58, 0x15000, v9
	global_load_ushort v54, v58, s[66:67]
	v_add_u32_e32 v59, 0x16c00, v9
	global_load_ushort v55, v59, s[66:67]
	v_add_u32_e32 v58, 0x18800, v9
	global_load_ushort v56, v58, s[66:67]
	v_add_u32_e32 v59, 0x1a400, v9
	global_load_ushort v57, v59, s[66:67]
	v_add_u32_e32 v9, 0x1c000, v9
	s_waitcnt vmcnt(32)
	v_lshlrev_b32_e32 v10, 16, v10
	v_lshlrev_b32_e32 v11, 16, v11
	v_lshlrev_b32_e32 v12, 16, v12
	v_lshlrev_b32_e32 v13, 16, v13
	v_lshlrev_b32_e32 v14, 16, v14
	v_lshlrev_b32_e32 v15, 16, v15
	v_lshlrev_b32_e32 v16, 16, v16
	v_lshlrev_b32_e32 v17, 16, v17
	v_lshlrev_b32_e32 v18, 16, v18
	v_lshlrev_b32_e32 v19, 16, v19
	v_lshlrev_b32_e32 v20, 16, v20
	v_lshlrev_b32_e32 v21, 16, v21
	v_lshlrev_b32_e32 v22, 16, v22
	v_lshlrev_b32_e32 v23, 16, v23
	v_lshlrev_b32_e32 v24, 16, v24
	v_lshlrev_b32_e32 v25, 16, v25
	v_add_f32_e32 v4, v4, v10
	v_add_f32_e32 v6, v6, v11
	v_add_f32_e32 v5, v5, v12
	v_add_f32_e32 v7, v7, v13
	v_add_f32_e32 v4, v4, v14
	v_add_f32_e32 v6, v6, v15
	v_add_f32_e32 v5, v5, v16
	v_add_f32_e32 v7, v7, v17
	v_add_f32_e32 v4, v4, v18
	v_add_f32_e32 v6, v6, v19
	v_add_f32_e32 v5, v5, v20
	v_add_f32_e32 v7, v7, v21
	v_add_f32_e32 v4, v4, v22
	v_add_f32_e32 v6, v6, v23
	v_add_f32_e32 v5, v5, v24
	v_add_f32_e32 v7, v7, v25
	v_mov_b32_e32 v58, v9
	global_load_ushort v10, v58, s[66:67]
	v_add_u32_e32 v59, 0x1c00, v9
	global_load_ushort v11, v59, s[66:67]
	v_add_u32_e32 v58, 0x3800, v9
	global_load_ushort v12, v58, s[66:67]
	v_add_u32_e32 v59, 0x5400, v9
	global_load_ushort v13, v59, s[66:67]
	v_add_u32_e32 v58, 0x7000, v9
	global_load_ushort v14, v58, s[66:67]
	v_add_u32_e32 v59, 0x8c00, v9
	global_load_ushort v15, v59, s[66:67]
	v_add_u32_e32 v58, 0xa800, v9
	global_load_ushort v16, v58, s[66:67]
	v_add_u32_e32 v59, 0xc400, v9
	global_load_ushort v17, v59, s[66:67]
	v_add_u32_e32 v58, 0xe000, v9
	global_load_ushort v18, v58, s[66:67]
	v_add_u32_e32 v59, 0xfc00, v9
	global_load_ushort v19, v59, s[66:67]
	v_add_u32_e32 v58, 0x11800, v9
	global_load_ushort v20, v58, s[66:67]
	v_add_u32_e32 v59, 0x13400, v9
	global_load_ushort v21, v59, s[66:67]
	v_add_u32_e32 v58, 0x15000, v9
	global_load_ushort v22, v58, s[66:67]
	v_add_u32_e32 v59, 0x16c00, v9
	global_load_ushort v23, v59, s[66:67]
	v_add_u32_e32 v58, 0x18800, v9
	global_load_ushort v24, v58, s[66:67]
	v_add_u32_e32 v59, 0x1a400, v9
	global_load_ushort v25, v59, s[66:67]
	v_add_u32_e32 v9, 0x1c000, v9
	s_waitcnt vmcnt(32)
	v_lshlrev_b32_e32 v26, 16, v26
	v_lshlrev_b32_e32 v27, 16, v27
	v_lshlrev_b32_e32 v28, 16, v28
	v_lshlrev_b32_e32 v29, 16, v29
	v_lshlrev_b32_e32 v30, 16, v30
	v_lshlrev_b32_e32 v31, 16, v31
	v_lshlrev_b32_e32 v32, 16, v32
	v_lshlrev_b32_e32 v33, 16, v33
	v_lshlrev_b32_e32 v34, 16, v34
	v_lshlrev_b32_e32 v35, 16, v35
	v_lshlrev_b32_e32 v36, 16, v36
	v_lshlrev_b32_e32 v37, 16, v37
	v_lshlrev_b32_e32 v38, 16, v38
	v_lshlrev_b32_e32 v39, 16, v39
	v_lshlrev_b32_e32 v40, 16, v40
	v_lshlrev_b32_e32 v41, 16, v41
	v_add_f32_e32 v4, v4, v26
	v_add_f32_e32 v6, v6, v27
	v_add_f32_e32 v5, v5, v28
	v_add_f32_e32 v7, v7, v29
	v_add_f32_e32 v4, v4, v30
	v_add_f32_e32 v6, v6, v31
	v_add_f32_e32 v5, v5, v32
	v_add_f32_e32 v7, v7, v33
	v_add_f32_e32 v4, v4, v34
	v_add_f32_e32 v6, v6, v35
	v_add_f32_e32 v5, v5, v36
	v_add_f32_e32 v7, v7, v37
	v_add_f32_e32 v4, v4, v38
	v_add_f32_e32 v6, v6, v39
	v_add_f32_e32 v5, v5, v40
	v_add_f32_e32 v7, v7, v41
	v_mov_b32_e32 v58, v9
	global_load_ushort v26, v58, s[66:67]
	v_add_u32_e32 v59, 0x1c00, v9
	global_load_ushort v27, v59, s[66:67]
	v_add_u32_e32 v58, 0x3800, v9
	global_load_ushort v28, v58, s[66:67]
	v_add_u32_e32 v59, 0x5400, v9
	global_load_ushort v29, v59, s[66:67]
	v_add_u32_e32 v58, 0x7000, v9
	global_load_ushort v30, v58, s[66:67]
	v_add_u32_e32 v59, 0x8c00, v9
	global_load_ushort v31, v59, s[66:67]
	v_add_u32_e32 v58, 0xa800, v9
	global_load_ushort v32, v58, s[66:67]
	v_add_u32_e32 v59, 0xc400, v9
	global_load_ushort v33, v59, s[66:67]
	v_add_u32_e32 v58, 0xe000, v9
	global_load_ushort v34, v58, s[66:67]
	v_add_u32_e32 v59, 0xfc00, v9
	global_load_ushort v35, v59, s[66:67]
	v_add_u32_e32 v58, 0x11800, v9
	global_load_ushort v36, v58, s[66:67]
	v_add_u32_e32 v59, 0x13400, v9
	global_load_ushort v37, v59, s[66:67]
	v_add_u32_e32 v58, 0x15000, v9
	global_load_ushort v38, v58, s[66:67]
	v_add_u32_e32 v59, 0x16c00, v9
	global_load_ushort v39, v59, s[66:67]
	v_add_u32_e32 v58, 0x18800, v9
	global_load_ushort v40, v58, s[66:67]
	v_add_u32_e32 v59, 0x1a400, v9
	global_load_ushort v41, v59, s[66:67]
	v_add_u32_e32 v9, 0x1c000, v9
	s_waitcnt vmcnt(32)
	v_lshlrev_b32_e32 v42, 16, v42
	v_lshlrev_b32_e32 v43, 16, v43
	v_lshlrev_b32_e32 v44, 16, v44
	v_lshlrev_b32_e32 v45, 16, v45
	v_lshlrev_b32_e32 v46, 16, v46
	v_lshlrev_b32_e32 v47, 16, v47
	v_lshlrev_b32_e32 v48, 16, v48
	v_lshlrev_b32_e32 v49, 16, v49
	v_lshlrev_b32_e32 v50, 16, v50
	v_lshlrev_b32_e32 v51, 16, v51
	v_lshlrev_b32_e32 v52, 16, v52
	v_lshlrev_b32_e32 v53, 16, v53
	v_lshlrev_b32_e32 v54, 16, v54
	v_lshlrev_b32_e32 v55, 16, v55
	v_lshlrev_b32_e32 v56, 16, v56
	v_lshlrev_b32_e32 v57, 16, v57
	v_add_f32_e32 v4, v4, v42
	v_add_f32_e32 v6, v6, v43
	v_add_f32_e32 v5, v5, v44
	v_add_f32_e32 v7, v7, v45
	v_add_f32_e32 v4, v4, v46
	v_add_f32_e32 v6, v6, v47
	v_add_f32_e32 v5, v5, v48
	v_add_f32_e32 v7, v7, v49
	v_add_f32_e32 v4, v4, v50
	v_add_f32_e32 v6, v6, v51
	v_add_f32_e32 v5, v5, v52
	v_add_f32_e32 v7, v7, v53
	v_add_f32_e32 v4, v4, v54
	v_add_f32_e32 v6, v6, v55
	v_add_f32_e32 v5, v5, v56
	v_add_f32_e32 v7, v7, v57
	v_mov_b32_e32 v58, v9
	global_load_ushort v42, v58, s[66:67]
	v_add_u32_e32 v59, 0x1c00, v9
	global_load_ushort v43, v59, s[66:67]
	v_add_u32_e32 v58, 0x3800, v9
	global_load_ushort v44, v58, s[66:67]
	v_add_u32_e32 v59, 0x5400, v9
	global_load_ushort v45, v59, s[66:67]
	v_add_u32_e32 v58, 0x7000, v9
	global_load_ushort v46, v58, s[66:67]
	v_add_u32_e32 v59, 0x8c00, v9
	global_load_ushort v47, v59, s[66:67]
	v_add_u32_e32 v58, 0xa800, v9
	global_load_ushort v48, v58, s[66:67]
	v_add_u32_e32 v59, 0xc400, v9
	global_load_ushort v49, v59, s[66:67]
	v_add_u32_e32 v58, 0xe000, v9
	global_load_ushort v50, v58, s[66:67]
	v_add_u32_e32 v59, 0xfc00, v9
	global_load_ushort v51, v59, s[66:67]
	v_add_u32_e32 v58, 0x11800, v9
	global_load_ushort v52, v58, s[66:67]
	v_add_u32_e32 v59, 0x13400, v9
	global_load_ushort v53, v59, s[66:67]
	v_add_u32_e32 v58, 0x15000, v9
	global_load_ushort v54, v58, s[66:67]
	v_add_u32_e32 v59, 0x16c00, v9
	global_load_ushort v55, v59, s[66:67]
	v_add_u32_e32 v58, 0x18800, v9
	global_load_ushort v56, v58, s[66:67]
	v_add_u32_e32 v59, 0x1a400, v9
	global_load_ushort v57, v59, s[66:67]
	v_add_u32_e32 v9, 0x1c000, v9
	s_waitcnt vmcnt(32)
	v_lshlrev_b32_e32 v10, 16, v10
	v_lshlrev_b32_e32 v11, 16, v11
	v_lshlrev_b32_e32 v12, 16, v12
	v_lshlrev_b32_e32 v13, 16, v13
	v_lshlrev_b32_e32 v14, 16, v14
	v_lshlrev_b32_e32 v15, 16, v15
	v_lshlrev_b32_e32 v16, 16, v16
	v_lshlrev_b32_e32 v17, 16, v17
	v_lshlrev_b32_e32 v18, 16, v18
	v_lshlrev_b32_e32 v19, 16, v19
	v_lshlrev_b32_e32 v20, 16, v20
	v_lshlrev_b32_e32 v21, 16, v21
	v_lshlrev_b32_e32 v22, 16, v22
	v_lshlrev_b32_e32 v23, 16, v23
	v_lshlrev_b32_e32 v24, 16, v24
	v_lshlrev_b32_e32 v25, 16, v25
	v_add_f32_e32 v4, v4, v10
	v_add_f32_e32 v6, v6, v11
	v_add_f32_e32 v5, v5, v12
	v_add_f32_e32 v7, v7, v13
	v_add_f32_e32 v4, v4, v14
	v_add_f32_e32 v6, v6, v15
	v_add_f32_e32 v5, v5, v16
	v_add_f32_e32 v7, v7, v17
	v_add_f32_e32 v4, v4, v18
	v_add_f32_e32 v6, v6, v19
	v_add_f32_e32 v5, v5, v20
	v_add_f32_e32 v7, v7, v21
	v_add_f32_e32 v4, v4, v22
	v_add_f32_e32 v6, v6, v23
	v_add_f32_e32 v5, v5, v24
	v_add_f32_e32 v7, v7, v25
	v_mov_b32_e32 v58, v9
	global_load_ushort v10, v58, s[66:67]
	v_add_u32_e32 v59, 0x1c00, v9
	global_load_ushort v11, v59, s[66:67]
	v_add_u32_e32 v58, 0x3800, v9
	global_load_ushort v12, v58, s[66:67]
	v_add_u32_e32 v59, 0x5400, v9
	global_load_ushort v13, v59, s[66:67]
	v_add_u32_e32 v58, 0x7000, v9
	global_load_ushort v14, v58, s[66:67]
	v_add_u32_e32 v59, 0x8c00, v9
	global_load_ushort v15, v59, s[66:67]
	v_add_u32_e32 v58, 0xa800, v9
	global_load_ushort v16, v58, s[66:67]
	v_add_u32_e32 v59, 0xc400, v9
	global_load_ushort v17, v59, s[66:67]
	v_add_u32_e32 v58, 0xe000, v9
	global_load_ushort v18, v58, s[66:67]
	v_add_u32_e32 v59, 0xfc00, v9
	global_load_ushort v19, v59, s[66:67]
	v_add_u32_e32 v58, 0x11800, v9
	global_load_ushort v20, v58, s[66:67]
	v_add_u32_e32 v59, 0x13400, v9
	global_load_ushort v21, v59, s[66:67]
	v_add_u32_e32 v58, 0x15000, v9
	global_load_ushort v22, v58, s[66:67]
	v_add_u32_e32 v59, 0x16c00, v9
	global_load_ushort v23, v59, s[66:67]
	v_add_u32_e32 v58, 0x18800, v9
	global_load_ushort v24, v58, s[66:67]
	v_add_u32_e32 v59, 0x1a400, v9
	global_load_ushort v25, v59, s[66:67]
	v_add_u32_e32 v9, 0x1c000, v9
	s_waitcnt vmcnt(32)
	v_lshlrev_b32_e32 v26, 16, v26
	v_lshlrev_b32_e32 v27, 16, v27
	v_lshlrev_b32_e32 v28, 16, v28
	v_lshlrev_b32_e32 v29, 16, v29
	v_lshlrev_b32_e32 v30, 16, v30
	v_lshlrev_b32_e32 v31, 16, v31
	v_lshlrev_b32_e32 v32, 16, v32
	v_lshlrev_b32_e32 v33, 16, v33
	v_lshlrev_b32_e32 v34, 16, v34
	v_lshlrev_b32_e32 v35, 16, v35
	v_lshlrev_b32_e32 v36, 16, v36
	v_lshlrev_b32_e32 v37, 16, v37
	v_lshlrev_b32_e32 v38, 16, v38
	v_lshlrev_b32_e32 v39, 16, v39
	v_lshlrev_b32_e32 v40, 16, v40
	v_lshlrev_b32_e32 v41, 16, v41
	v_add_f32_e32 v4, v4, v26
	v_add_f32_e32 v6, v6, v27
	v_add_f32_e32 v5, v5, v28
	v_add_f32_e32 v7, v7, v29
	v_add_f32_e32 v4, v4, v30
	v_add_f32_e32 v6, v6, v31
	v_add_f32_e32 v5, v5, v32
	v_add_f32_e32 v7, v7, v33
	v_add_f32_e32 v4, v4, v34
	v_add_f32_e32 v6, v6, v35
	v_add_f32_e32 v5, v5, v36
	v_add_f32_e32 v7, v7, v37
	v_add_f32_e32 v4, v4, v38
	v_add_f32_e32 v6, v6, v39
	v_add_f32_e32 v5, v5, v40
	v_add_f32_e32 v7, v7, v41
	v_mov_b32_e32 v58, v9
	global_load_ushort v26, v58, s[66:67]
	v_add_u32_e32 v59, 0x1c00, v9
	global_load_ushort v27, v59, s[66:67]
	v_add_u32_e32 v58, 0x3800, v9
	global_load_ushort v28, v58, s[66:67]
	v_add_u32_e32 v59, 0x5400, v9
	global_load_ushort v29, v59, s[66:67]
	v_add_u32_e32 v58, 0x7000, v9
	global_load_ushort v30, v58, s[66:67]
	v_add_u32_e32 v59, 0x8c00, v9
	global_load_ushort v31, v59, s[66:67]
	v_add_u32_e32 v58, 0xa800, v9
	global_load_ushort v32, v58, s[66:67]
	v_add_u32_e32 v59, 0xc400, v9
	global_load_ushort v33, v59, s[66:67]
	v_add_u32_e32 v58, 0xe000, v9
	global_load_ushort v34, v58, s[66:67]
	v_add_u32_e32 v59, 0xfc00, v9
	global_load_ushort v35, v59, s[66:67]
	v_add_u32_e32 v58, 0x11800, v9
	global_load_ushort v36, v58, s[66:67]
	v_add_u32_e32 v59, 0x13400, v9
	global_load_ushort v37, v59, s[66:67]
	v_add_u32_e32 v58, 0x15000, v9
	global_load_ushort v38, v58, s[66:67]
	v_add_u32_e32 v59, 0x16c00, v9
	global_load_ushort v39, v59, s[66:67]
	v_add_u32_e32 v58, 0x18800, v9
	global_load_ushort v40, v58, s[66:67]
	v_add_u32_e32 v59, 0x1a400, v9
	global_load_ushort v41, v59, s[66:67]
	v_add_u32_e32 v9, 0x1c000, v9
	s_waitcnt vmcnt(32)
	v_lshlrev_b32_e32 v42, 16, v42
	v_lshlrev_b32_e32 v43, 16, v43
	v_lshlrev_b32_e32 v44, 16, v44
	v_lshlrev_b32_e32 v45, 16, v45
	v_lshlrev_b32_e32 v46, 16, v46
	v_lshlrev_b32_e32 v47, 16, v47
	v_lshlrev_b32_e32 v48, 16, v48
	v_lshlrev_b32_e32 v49, 16, v49
	v_lshlrev_b32_e32 v50, 16, v50
	v_lshlrev_b32_e32 v51, 16, v51
	v_lshlrev_b32_e32 v52, 16, v52
	v_lshlrev_b32_e32 v53, 16, v53
	v_lshlrev_b32_e32 v54, 16, v54
	v_lshlrev_b32_e32 v55, 16, v55
	v_lshlrev_b32_e32 v56, 16, v56
	v_lshlrev_b32_e32 v57, 16, v57
	v_add_f32_e32 v4, v4, v42
	v_add_f32_e32 v6, v6, v43
	v_add_f32_e32 v5, v5, v44
	v_add_f32_e32 v7, v7, v45
	v_add_f32_e32 v4, v4, v46
	v_add_f32_e32 v6, v6, v47
	v_add_f32_e32 v5, v5, v48
	v_add_f32_e32 v7, v7, v49
	v_add_f32_e32 v4, v4, v50
	v_add_f32_e32 v6, v6, v51
	v_add_f32_e32 v5, v5, v52
	v_add_f32_e32 v7, v7, v53
	v_add_f32_e32 v4, v4, v54
	v_add_f32_e32 v6, v6, v55
	v_add_f32_e32 v5, v5, v56
	v_add_f32_e32 v7, v7, v57
	v_mov_b32_e32 v58, v9
	global_load_ushort v42, v58, s[66:67]
	v_add_u32_e32 v59, 0x1c00, v9
	global_load_ushort v43, v59, s[66:67]
	v_add_u32_e32 v58, 0x3800, v9
	global_load_ushort v44, v58, s[66:67]
	v_add_u32_e32 v59, 0x5400, v9
	global_load_ushort v45, v59, s[66:67]
	v_add_u32_e32 v58, 0x7000, v9
	global_load_ushort v46, v58, s[66:67]
	v_add_u32_e32 v59, 0x8c00, v9
	global_load_ushort v47, v59, s[66:67]
	v_add_u32_e32 v58, 0xa800, v9
	global_load_ushort v48, v58, s[66:67]
	v_add_u32_e32 v59, 0xc400, v9
	global_load_ushort v49, v59, s[66:67]
	v_add_u32_e32 v58, 0xe000, v9
	global_load_ushort v50, v58, s[66:67]
	v_add_u32_e32 v59, 0xfc00, v9
	global_load_ushort v51, v59, s[66:67]
	v_add_u32_e32 v58, 0x11800, v9
	global_load_ushort v52, v58, s[66:67]
	v_add_u32_e32 v59, 0x13400, v9
	global_load_ushort v53, v59, s[66:67]
	v_add_u32_e32 v58, 0x15000, v9
	global_load_ushort v54, v58, s[66:67]
	v_add_u32_e32 v59, 0x16c00, v9
	global_load_ushort v55, v59, s[66:67]
	v_add_u32_e32 v58, 0x18800, v9
	global_load_ushort v56, v58, s[66:67]
	v_add_u32_e32 v59, 0x1a400, v9
	global_load_ushort v57, v59, s[66:67]
	v_add_u32_e32 v9, 0x1c000, v9
	s_waitcnt vmcnt(32)
	v_lshlrev_b32_e32 v10, 16, v10
	v_lshlrev_b32_e32 v11, 16, v11
	v_lshlrev_b32_e32 v12, 16, v12
	v_lshlrev_b32_e32 v13, 16, v13
	v_lshlrev_b32_e32 v14, 16, v14
	v_lshlrev_b32_e32 v15, 16, v15
	v_lshlrev_b32_e32 v16, 16, v16
	v_lshlrev_b32_e32 v17, 16, v17
	v_lshlrev_b32_e32 v18, 16, v18
	v_lshlrev_b32_e32 v19, 16, v19
	v_lshlrev_b32_e32 v20, 16, v20
	v_lshlrev_b32_e32 v21, 16, v21
	v_lshlrev_b32_e32 v22, 16, v22
	v_lshlrev_b32_e32 v23, 16, v23
	v_lshlrev_b32_e32 v24, 16, v24
	v_lshlrev_b32_e32 v25, 16, v25
	v_add_f32_e32 v4, v4, v10
	v_add_f32_e32 v6, v6, v11
	v_add_f32_e32 v5, v5, v12
	v_add_f32_e32 v7, v7, v13
	v_add_f32_e32 v4, v4, v14
	v_add_f32_e32 v6, v6, v15
	v_add_f32_e32 v5, v5, v16
	v_add_f32_e32 v7, v7, v17
	v_add_f32_e32 v4, v4, v18
	v_add_f32_e32 v6, v6, v19
	v_add_f32_e32 v5, v5, v20
	v_add_f32_e32 v7, v7, v21
	v_add_f32_e32 v4, v4, v22
	v_add_f32_e32 v6, v6, v23
	v_add_f32_e32 v5, v5, v24
	v_add_f32_e32 v7, v7, v25
	v_mov_b32_e32 v58, v9
	global_load_ushort v10, v58, s[66:67]
	v_add_u32_e32 v59, 0x1c00, v9
	global_load_ushort v11, v59, s[66:67]
	v_add_u32_e32 v58, 0x3800, v9
	global_load_ushort v12, v58, s[66:67]
	v_add_u32_e32 v59, 0x5400, v9
	global_load_ushort v13, v59, s[66:67]
	v_add_u32_e32 v58, 0x7000, v9
	global_load_ushort v14, v58, s[66:67]
	v_add_u32_e32 v59, 0x8c00, v9
	global_load_ushort v15, v59, s[66:67]
	v_add_u32_e32 v58, 0xa800, v9
	global_load_ushort v16, v58, s[66:67]
	v_add_u32_e32 v59, 0xc400, v9
	global_load_ushort v17, v59, s[66:67]
	v_add_u32_e32 v58, 0xe000, v9
	global_load_ushort v18, v58, s[66:67]
	v_add_u32_e32 v59, 0xfc00, v9
	global_load_ushort v19, v59, s[66:67]
	v_add_u32_e32 v58, 0x11800, v9
	global_load_ushort v20, v58, s[66:67]
	v_add_u32_e32 v59, 0x13400, v9
	global_load_ushort v21, v59, s[66:67]
	v_add_u32_e32 v58, 0x15000, v9
	global_load_ushort v22, v58, s[66:67]
	v_add_u32_e32 v59, 0x16c00, v9
	global_load_ushort v23, v59, s[66:67]
	v_add_u32_e32 v58, 0x18800, v9
	global_load_ushort v24, v58, s[66:67]
	v_add_u32_e32 v59, 0x1a400, v9
	global_load_ushort v25, v59, s[66:67]
	v_add_u32_e32 v9, 0x1c000, v9
	s_waitcnt vmcnt(32)
	v_lshlrev_b32_e32 v26, 16, v26
	v_lshlrev_b32_e32 v27, 16, v27
	v_lshlrev_b32_e32 v28, 16, v28
	v_lshlrev_b32_e32 v29, 16, v29
	v_lshlrev_b32_e32 v30, 16, v30
	v_lshlrev_b32_e32 v31, 16, v31
	v_lshlrev_b32_e32 v32, 16, v32
	v_lshlrev_b32_e32 v33, 16, v33
	v_lshlrev_b32_e32 v34, 16, v34
	v_lshlrev_b32_e32 v35, 16, v35
	v_lshlrev_b32_e32 v36, 16, v36
	v_lshlrev_b32_e32 v37, 16, v37
	v_lshlrev_b32_e32 v38, 16, v38
	v_lshlrev_b32_e32 v39, 16, v39
	v_lshlrev_b32_e32 v40, 16, v40
	v_lshlrev_b32_e32 v41, 16, v41
	v_add_f32_e32 v4, v4, v26
	v_add_f32_e32 v6, v6, v27
	v_add_f32_e32 v5, v5, v28
	v_add_f32_e32 v7, v7, v29
	v_add_f32_e32 v4, v4, v30
	v_add_f32_e32 v6, v6, v31
	v_add_f32_e32 v5, v5, v32
	v_add_f32_e32 v7, v7, v33
	v_add_f32_e32 v4, v4, v34
	v_add_f32_e32 v6, v6, v35
	v_add_f32_e32 v5, v5, v36
	v_add_f32_e32 v7, v7, v37
	v_add_f32_e32 v4, v4, v38
	v_add_f32_e32 v6, v6, v39
	v_add_f32_e32 v5, v5, v40
	v_add_f32_e32 v7, v7, v41
	s_waitcnt vmcnt(16)
	v_lshlrev_b32_e32 v42, 16, v42
	v_lshlrev_b32_e32 v43, 16, v43
	v_lshlrev_b32_e32 v44, 16, v44
	v_lshlrev_b32_e32 v45, 16, v45
	v_lshlrev_b32_e32 v46, 16, v46
	v_lshlrev_b32_e32 v47, 16, v47
	v_lshlrev_b32_e32 v48, 16, v48
	v_lshlrev_b32_e32 v49, 16, v49
	v_lshlrev_b32_e32 v50, 16, v50
	v_lshlrev_b32_e32 v51, 16, v51
	v_lshlrev_b32_e32 v52, 16, v52
	v_lshlrev_b32_e32 v53, 16, v53
	v_lshlrev_b32_e32 v54, 16, v54
	v_lshlrev_b32_e32 v55, 16, v55
	v_lshlrev_b32_e32 v56, 16, v56
	v_lshlrev_b32_e32 v57, 16, v57
	v_add_f32_e32 v4, v4, v42
	v_add_f32_e32 v6, v6, v43
	v_add_f32_e32 v5, v5, v44
	v_add_f32_e32 v7, v7, v45
	v_add_f32_e32 v4, v4, v46
	v_add_f32_e32 v6, v6, v47
	v_add_f32_e32 v5, v5, v48
	v_add_f32_e32 v7, v7, v49
	v_add_f32_e32 v4, v4, v50
	v_add_f32_e32 v6, v6, v51
	v_add_f32_e32 v5, v5, v52
	v_add_f32_e32 v7, v7, v53
	v_add_f32_e32 v4, v4, v54
	v_add_f32_e32 v6, v6, v55
	v_add_f32_e32 v5, v5, v56
	v_add_f32_e32 v7, v7, v57
	s_waitcnt vmcnt(0)
	v_lshlrev_b32_e32 v10, 16, v10
	v_lshlrev_b32_e32 v11, 16, v11
	v_lshlrev_b32_e32 v12, 16, v12
	v_lshlrev_b32_e32 v13, 16, v13
	v_lshlrev_b32_e32 v14, 16, v14
	v_lshlrev_b32_e32 v15, 16, v15
	v_lshlrev_b32_e32 v16, 16, v16
	v_lshlrev_b32_e32 v17, 16, v17
	v_lshlrev_b32_e32 v18, 16, v18
	v_lshlrev_b32_e32 v19, 16, v19
	v_lshlrev_b32_e32 v20, 16, v20
	v_lshlrev_b32_e32 v21, 16, v21
	v_lshlrev_b32_e32 v22, 16, v22
	v_lshlrev_b32_e32 v23, 16, v23
	v_lshlrev_b32_e32 v24, 16, v24
	v_lshlrev_b32_e32 v25, 16, v25
	v_add_f32_e32 v4, v4, v10
	v_add_f32_e32 v6, v6, v11
	v_add_f32_e32 v5, v5, v12
	v_add_f32_e32 v7, v7, v13
	v_add_f32_e32 v4, v4, v14
	v_add_f32_e32 v6, v6, v15
	v_add_f32_e32 v5, v5, v16
	v_add_f32_e32 v7, v7, v17
	v_add_f32_e32 v4, v4, v18
	v_add_f32_e32 v6, v6, v19
	v_add_f32_e32 v5, v5, v20
	v_add_f32_e32 v7, v7, v21
	v_add_f32_e32 v4, v4, v22
	v_add_f32_e32 v6, v6, v23
	v_add_f32_e32 v5, v5, v24
	v_add_f32_e32 v7, v7, v25
	v_lshl_add_u32 v2, s42, 2, v69
	v_pk_add_f32 v[4:5], v[4:5], v[6:7]
	v_ashrrev_i32_e32 v3, 31, v2
	v_add_f32_e32 v0, v4, v5
	v_readlane_b32 s12, v253, 2
	v_mul_f32_e32 v0, 0x3b800000, v0
	v_lshlrev_b64 v[2:3], 7, v[2:3]
	v_readlane_b32 s24, v253, 14
	v_readlane_b32 s25, v253, 15
	v_cvt_pk_bf16_f32 v4, v0, s0
	v_readlane_b32 s23, v253, 13
	v_readlane_b32 s26, v253, 16
	v_readlane_b32 s27, v253, 17
	v_lshl_add_u64 v[2:3], s[24:25], 0, v[2:3]
	v_lshlrev_b32_e32 v0, 1, v8
	v_lshl_add_u64 v[2:3], v[2:3], 0, v[0:1]
	s_mov_b32 s23, 0x800000
	s_movk_i32 s24, 0xf00
	s_movk_i32 s25, 0x104
	s_mov_b64 s[26:27], 0x400c0
	v_readlane_b32 s13, v253, 3
	v_readlane_b32 s14, v253, 4
	v_readlane_b32 s15, v253, 5
	v_readlane_b32 s16, v253, 6
	v_readlane_b32 s17, v253, 7
	v_readlane_b32 s18, v253, 8
	v_readlane_b32 s19, v253, 9
	v_readlane_b32 s20, v253, 10
	v_readlane_b32 s21, v253, 11
	v_readlane_b32 s22, v253, 12
	global_store_short v[2:3], v4, off
